# v095 + max-reuse MFMA issue order (accumulator chains + shared source at every quad boundary) also in the K/V projection GEMM of P0b
# speedup vs baseline: 1.0038x; 1.0038x over previous
; #define PG8_STAGE(bufoff, gbase, voff) do { _Pragma("unroll") for (int _i = 0; _i < 2; ++_i) \
;         __builtin_amdgcn_global_load_lds((const unsigned*)((const char*)(gbase) + (voff)[_i]), (PG8_LAS unsigned*)(lds + (bufoff) + ldsw + _i * 8192), 16, 0, 0); } while (0)
; #define PG8_LDA(dst, b, h) do { _Pragma("unroll") for (int m = 0; m < 4; ++m) _Pragma("unroll") for (int k = 0; k < 2; ++k) dst[m][k] = *(const PG8_LAS bf16x8*)(lds + PG8_SA(b, h) + aoff + m * 2048 + k * 1024); } while (0)
; #define PG8_LDB(dst, b, h) do { _Pragma("unroll") for (int n = 0; n < 2; ++n) _Pragma("unroll") for (int k = 0; k < 2; ++k) dst[n][k] = *(const PG8_LAS bf16x8*)(lds + PG8_SB(b, h) + boff + n * 2048 + k * 1024); } while (0)
; #define PG8_MMA(ai, bj, At, Bt) do { __builtin_amdgcn_s_setprio(1); _Pragma("unroll") for (int m = 0; m < 4; ++m) _Pragma("unroll") for (int n = 0; n < 2; ++n) _Pragma("unroll") for (int k = 0; k < 2; ++k) \
;         acc[ai][bj][m][n] = __builtin_amdgcn_mfma_f32_16x16x32_bf16(Bt[n][k], At[m][k], acc[ai][bj][m][n], 0, 0, 0); __builtin_amdgcn_s_setprio(0); } while (0)
; #define PG8_WAIT_V(n) asm volatile("s_waitcnt vmcnt(" #n ")" ::: "memory")
; #define PG8_WAIT_L(n) asm volatile("s_waitcnt lgkmcnt(" #n ")" ::: "memory")
; #define PG8_BAR __builtin_amdgcn_s_barrier()
; #define PG8_SCHED __builtin_amdgcn_sched_barrier(0)
; template <class Epi, class Sched, bool ALIGN_EPI = false, bool SP2 = false, bool RS = false, bool BPRE = false>
; __device__ __forceinline__ void gemm_phase(PG8_LAS unsigned char* lds, const Gemm g, const Sched& S, const Epi& E, const float* rs_ss = nullptr, PG8_LAS float* rs_tab = nullptr) {
;     ...
;             PG8_LDB(B0, 0, 0); PG8_LDB(B1, 0, 1); PG8_SCHED; PG8_LDA(At, 0, 0); PG8_STAGE(PG8_SA(1, 1), a1 + hstep, voffA);
;             PG8_WAIT_V(8); PG8_WAIT_L(0); PG8_BAR; PG8_MMA(0, 0, At, B0); PG8_MMA(0, 1, At, B1); PG8_BAR; PG8_SCHED;
;             PG8_LDA(At, 0, 1); PG8_STAGE(PG8_SB(0, 0), b2, voffB); PG8_STAGE(PG8_SB(0, 1), b2 + hstep, voffB); PG8_STAGE(PG8_SA(0, 0), a2, voffA);
.LBB0_129:
	ds_read_b128 v[148:151], v137
	ds_read_b128 v[152:155], v137 offset:1024
	ds_read_b128 v[156:159], v137 offset:2048
	ds_read_b128 v[160:163], v137 offset:3072
	ds_read_b128 v[164:167], v144
	ds_read_b128 v[168:171], v144 offset:1024
	ds_read_b128 v[172:175], v144 offset:2048
	ds_read_b128 v[176:179], v144 offset:3072
	s_add_u32 s16, s12, s14
	s_addc_u32 s17, s13, s15
	s_add_u32 s16, s16, 0x2808000
	s_addc_u32 s17, s17, 0
	s_add_u32 s18, s54, s14
	s_addc_u32 s19, s55, s15
	s_cmp_eq_u32 s14, 0x78000
	s_cselect_b32 s20, s10, s16
	s_cselect_b32 s21, s11, s17
	s_cselect_b32 s18, s6, s18
	s_cselect_b32 s19, s7, s19
	s_add_u32 s16, s20, 0x4000
	s_addc_u32 s17, s21, 0
	s_mov_b32 m0, s57
	v_lshl_add_u64 v[180:181], v[140:141], 0, s[14:15]
	ds_read_b128 v[182:185], v145
	ds_read_b128 v[186:189], v145 offset:1024
	ds_read_b128 v[190:193], v145 offset:2048
	ds_read_b128 v[194:197], v145 offset:3072
	ds_read_b128 v[198:201], v145 offset:4096
	ds_read_b128 v[202:205], v145 offset:5120
	ds_read_b128 v[206:209], v145 offset:6144
	ds_read_b128 v[210:213], v145 offset:7168
	global_load_lds_dwordx4 v[180:181], off
	v_lshl_add_u64 v[180:181], v[142:143], 0, s[14:15]
	s_mov_b32 m0, s58
	s_nop 0
	global_load_lds_dwordx4 v[180:181], off
	s_waitcnt vmcnt(8)
	s_waitcnt lgkmcnt(0)
	s_barrier
	s_setprio 1
	s_waitcnt lgkmcnt(0)
	v_mfma_f32_16x16x32_bf16 v[126:129], v[148:151], v[182:185], v[126:129]
	v_mfma_f32_16x16x32_bf16 v[126:129], v[152:155], v[186:189], v[126:129]
	v_mfma_f32_16x16x32_bf16 v[122:125], v[160:163], v[186:189], v[122:125]
	v_mfma_f32_16x16x32_bf16 v[122:125], v[156:159], v[182:185], v[122:125]
	v_mfma_f32_16x16x32_bf16 v[110:113], v[156:159], v[190:193], v[110:113]
	v_mfma_f32_16x16x32_bf16 v[110:113], v[160:163], v[194:197], v[110:113]
	v_mfma_f32_16x16x32_bf16 v[118:121], v[152:155], v[194:197], v[118:121]
	v_mfma_f32_16x16x32_bf16 v[118:121], v[148:151], v[190:193], v[118:121]
	v_mfma_f32_16x16x32_bf16 v[102:105], v[148:151], v[198:201], v[102:105]
	v_mfma_f32_16x16x32_bf16 v[102:105], v[152:155], v[202:205], v[102:105]
	v_mfma_f32_16x16x32_bf16 v[94:97], v[160:163], v[202:205], v[94:97]
	v_mfma_f32_16x16x32_bf16 v[94:97], v[156:159], v[198:201], v[94:97]
	v_mfma_f32_16x16x32_bf16 v[78:81], v[156:159], v[206:209], v[78:81]
	v_mfma_f32_16x16x32_bf16 v[78:81], v[160:163], v[210:213], v[78:81]
	v_mfma_f32_16x16x32_bf16 v[86:89], v[152:155], v[210:213], v[86:89]
	v_mfma_f32_16x16x32_bf16 v[86:89], v[148:151], v[206:209], v[86:89]
	s_setprio 0
	s_setprio 1
	v_mfma_f32_16x16x32_bf16 v[70:73], v[164:167], v[206:209], v[70:73]
	v_mfma_f32_16x16x32_bf16 v[70:73], v[168:171], v[210:213], v[70:73]
	v_mfma_f32_16x16x32_bf16 v[66:69], v[176:179], v[210:213], v[66:69]
	v_mfma_f32_16x16x32_bf16 v[66:69], v[172:175], v[206:209], v[66:69]
	v_mfma_f32_16x16x32_bf16 v[74:77], v[172:175], v[198:201], v[74:77]
	v_mfma_f32_16x16x32_bf16 v[74:77], v[176:179], v[202:205], v[74:77]
	v_mfma_f32_16x16x32_bf16 v[82:85], v[168:171], v[202:205], v[82:85]
	v_mfma_f32_16x16x32_bf16 v[82:85], v[164:167], v[198:201], v[82:85]
	v_mfma_f32_16x16x32_bf16 v[98:101], v[164:167], v[190:193], v[98:101]
	v_mfma_f32_16x16x32_bf16 v[98:101], v[168:171], v[194:197], v[98:101]
	v_mfma_f32_16x16x32_bf16 v[90:93], v[176:179], v[194:197], v[90:93]
	v_mfma_f32_16x16x32_bf16 v[90:93], v[172:175], v[190:193], v[90:93]
	v_mfma_f32_16x16x32_bf16 v[106:109], v[172:175], v[182:185], v[106:109]
	v_mfma_f32_16x16x32_bf16 v[106:109], v[176:179], v[186:189], v[106:109]
	v_mfma_f32_16x16x32_bf16 v[114:117], v[168:171], v[186:189], v[114:117]
	v_mfma_f32_16x16x32_bf16 v[114:117], v[164:167], v[182:185], v[114:117]
	s_setprio 0
	s_barrier
	s_mov_b32 m0, s59
	v_lshl_add_u64 v[180:181], s[18:19], 0, v[132:133]
	s_add_u32 s76, s18, 0x80000
	ds_read_b128 v[182:185], v145 offset:16384
	ds_read_b128 v[186:189], v145 offset:17408
	ds_read_b128 v[190:193], v145 offset:18432
	ds_read_b128 v[194:197], v145 offset:19456
	ds_read_b128 v[198:201], v145 offset:20480
	ds_read_b128 v[202:205], v145 offset:21504
	ds_read_b128 v[206:209], v145 offset:22528
	ds_read_b128 v[210:213], v145 offset:23552
	global_load_lds_dwordx4 v[180:181], off
	v_lshl_add_u64 v[180:181], s[18:19], 0, v[138:139]
	s_mov_b32 m0, s60
	s_addc_u32 s77, s19, 0
	global_load_lds_dwordx4 v[180:181], off
	v_lshl_add_u64 v[180:181], s[76:77], 0, v[132:133]
	s_mov_b32 m0, s61
	s_nop 0
	global_load_lds_dwordx4 v[180:181], off
	v_lshl_add_u64 v[180:181], s[76:77], 0, v[138:139]
	s_mov_b32 m0, s70
	s_nop 0
	global_load_lds_dwordx4 v[180:181], off
	v_lshl_add_u64 v[180:181], s[20:21], 0, v[130:131]
	s_mov_b32 m0, s1
	s_nop 0
	global_load_lds_dwordx4 v[180:181], off
	v_lshl_add_u64 v[180:181], s[20:21], 0, v[134:135]
	s_mov_b32 m0, s5
	s_nop 0
	global_load_lds_dwordx4 v[180:181], off
	s_waitcnt vmcnt(8)
	s_waitcnt lgkmcnt(0)
	s_barrier
; #define PG8_STAGE(bufoff, gbase, voff) do { _Pragma("unroll") for (int _i = 0; _i < 2; ++_i) \
;         __builtin_amdgcn_global_load_lds((const unsigned*)((const char*)(gbase) + (voff)[_i]), (PG8_LAS unsigned*)(lds + (bufoff) + ldsw + _i * 8192), 16, 0, 0); } while (0)
; #define PG8_LDA(dst, b, h) do { _Pragma("unroll") for (int m = 0; m < 4; ++m) _Pragma("unroll") for (int k = 0; k < 2; ++k) dst[m][k] = *(const PG8_LAS bf16x8*)(lds + PG8_SA(b, h) + aoff + m * 2048 + k * 1024); } while (0)
; #define PG8_LDB(dst, b, h) do { _Pragma("unroll") for (int n = 0; n < 2; ++n) _Pragma("unroll") for (int k = 0; k < 2; ++k) dst[n][k] = *(const PG8_LAS bf16x8*)(lds + PG8_SB(b, h) + boff + n * 2048 + k * 1024); } while (0)
; #define PG8_MMA(ai, bj, At, Bt) do { __builtin_amdgcn_s_setprio(1); _Pragma("unroll") for (int m = 0; m < 4; ++m) _Pragma("unroll") for (int n = 0; n < 2; ++n) _Pragma("unroll") for (int k = 0; k < 2; ++k) \
;         acc[ai][bj][m][n] = __builtin_amdgcn_mfma_f32_16x16x32_bf16(Bt[n][k], At[m][k], acc[ai][bj][m][n], 0, 0, 0); __builtin_amdgcn_s_setprio(0); } while (0)
; #define PG8_WAIT_V(n) asm volatile("s_waitcnt vmcnt(" #n ")" ::: "memory")
; #define PG8_WAIT_L(n) asm volatile("s_waitcnt lgkmcnt(" #n ")" ::: "memory")
; #define PG8_BAR __builtin_amdgcn_s_barrier()
; #define PG8_SCHED __builtin_amdgcn_sched_barrier(0)
; template <class Epi, class Sched, bool ALIGN_EPI = false, bool SP2 = false, bool RS = false, bool BPRE = false>
; __device__ __forceinline__ void gemm_phase(PG8_LAS unsigned char* lds, const Gemm g, const Sched& S, const Epi& E, const float* rs_ss = nullptr, PG8_LAS float* rs_tab = nullptr) {
;     ...
;             PG8_WAIT_V(8); PG8_WAIT_L(0); PG8_BAR; PG8_MMA(1, 0, At, B0); PG8_MMA(1, 1, At, B1); PG8_BAR; PG8_SCHED;
;             PG8_LDB(B0, 1, 0); PG8_LDB(B1, 1, 1); PG8_SCHED; PG8_LDA(At, 1, 0); PG8_STAGE(PG8_SA(0, 1), a2 + hstep, voffA);
;             PG8_WAIT_V(8); PG8_WAIT_L(0); PG8_BAR; PG8_MMA(0, 0, At, B0); PG8_MMA(0, 1, At, B1); PG8_BAR; PG8_SCHED;
	s_setprio 1
	s_waitcnt lgkmcnt(0)
	v_mfma_f32_16x16x32_bf16 v[62:65], v[148:151], v[182:185], v[62:65]
	v_mfma_f32_16x16x32_bf16 v[62:65], v[152:155], v[186:189], v[62:65]
	v_mfma_f32_16x16x32_bf16 v[58:61], v[160:163], v[186:189], v[58:61]
	v_mfma_f32_16x16x32_bf16 v[58:61], v[156:159], v[182:185], v[58:61]
	v_mfma_f32_16x16x32_bf16 v[46:49], v[156:159], v[190:193], v[46:49]
	v_mfma_f32_16x16x32_bf16 v[46:49], v[160:163], v[194:197], v[46:49]
	v_mfma_f32_16x16x32_bf16 v[54:57], v[152:155], v[194:197], v[54:57]
	v_mfma_f32_16x16x32_bf16 v[54:57], v[148:151], v[190:193], v[54:57]
	v_mfma_f32_16x16x32_bf16 v[38:41], v[148:151], v[198:201], v[38:41]
	v_mfma_f32_16x16x32_bf16 v[38:41], v[152:155], v[202:205], v[38:41]
	v_mfma_f32_16x16x32_bf16 v[30:33], v[160:163], v[202:205], v[30:33]
	v_mfma_f32_16x16x32_bf16 v[30:33], v[156:159], v[198:201], v[30:33]
	v_mfma_f32_16x16x32_bf16 v[14:17], v[156:159], v[206:209], v[14:17]
	v_mfma_f32_16x16x32_bf16 v[14:17], v[160:163], v[210:213], v[14:17]
	v_mfma_f32_16x16x32_bf16 v[22:25], v[152:155], v[210:213], v[22:25]
	v_mfma_f32_16x16x32_bf16 v[22:25], v[148:151], v[206:209], v[22:25]
	s_setprio 0
	s_setprio 1
	v_mfma_f32_16x16x32_bf16 v[6:9], v[164:167], v[206:209], v[6:9]
	v_mfma_f32_16x16x32_bf16 v[6:9], v[168:171], v[210:213], v[6:9]
	v_mfma_f32_16x16x32_bf16 v[2:5], v[176:179], v[210:213], v[2:5]
	v_mfma_f32_16x16x32_bf16 v[2:5], v[172:175], v[206:209], v[2:5]
	v_mfma_f32_16x16x32_bf16 v[10:13], v[172:175], v[198:201], v[10:13]
	v_mfma_f32_16x16x32_bf16 v[10:13], v[176:179], v[202:205], v[10:13]
	v_mfma_f32_16x16x32_bf16 v[18:21], v[168:171], v[202:205], v[18:21]
	v_mfma_f32_16x16x32_bf16 v[18:21], v[164:167], v[198:201], v[18:21]
	v_mfma_f32_16x16x32_bf16 v[34:37], v[164:167], v[190:193], v[34:37]
	v_mfma_f32_16x16x32_bf16 v[34:37], v[168:171], v[194:197], v[34:37]
	v_mfma_f32_16x16x32_bf16 v[26:29], v[176:179], v[194:197], v[26:29]
	v_mfma_f32_16x16x32_bf16 v[26:29], v[172:175], v[190:193], v[26:29]
	v_mfma_f32_16x16x32_bf16 v[42:45], v[172:175], v[182:185], v[42:45]
	v_mfma_f32_16x16x32_bf16 v[42:45], v[176:179], v[186:189], v[42:45]
	v_mfma_f32_16x16x32_bf16 v[50:53], v[168:171], v[186:189], v[50:53]
	v_mfma_f32_16x16x32_bf16 v[50:53], v[164:167], v[182:185], v[50:53]
	s_setprio 0
	s_barrier
	ds_read_b128 v[148:151], v146
	ds_read_b128 v[152:155], v146 offset:1024
	ds_read_b128 v[156:159], v146 offset:2048
	ds_read_b128 v[160:163], v146 offset:3072
	ds_read_b128 v[164:167], v147
	ds_read_b128 v[168:171], v147 offset:1024
	ds_read_b128 v[172:175], v147 offset:2048
	ds_read_b128 v[176:179], v147 offset:3072
	s_add_u32 s20, s20, 0x80000
	s_addc_u32 s21, s21, 0
	s_mov_b32 m0, s44
	v_lshl_add_u64 v[180:181], s[20:21], 0, v[130:131]
	ds_read_b128 v[182:185], v145 offset:32768
	ds_read_b128 v[186:189], v145 offset:33792
	ds_read_b128 v[190:193], v145 offset:34816
	ds_read_b128 v[194:197], v145 offset:35840
	ds_read_b128 v[198:201], v145 offset:36864
	ds_read_b128 v[202:205], v145 offset:37888
	ds_read_b128 v[206:209], v145 offset:38912
	ds_read_b128 v[210:213], v145 offset:39936
	global_load_lds_dwordx4 v[180:181], off
	v_lshl_add_u64 v[180:181], s[20:21], 0, v[134:135]
	s_mov_b32 m0, s45
	s_nop 0
	global_load_lds_dwordx4 v[180:181], off
	s_waitcnt vmcnt(8)
	s_waitcnt lgkmcnt(0)
	s_barrier
	s_setprio 1
	s_waitcnt lgkmcnt(0)
	v_mfma_f32_16x16x32_bf16 v[126:129], v[148:151], v[182:185], v[126:129]
	v_mfma_f32_16x16x32_bf16 v[126:129], v[152:155], v[186:189], v[126:129]
	v_mfma_f32_16x16x32_bf16 v[122:125], v[160:163], v[186:189], v[122:125]
	v_mfma_f32_16x16x32_bf16 v[122:125], v[156:159], v[182:185], v[122:125]
	v_mfma_f32_16x16x32_bf16 v[110:113], v[156:159], v[190:193], v[110:113]
	v_mfma_f32_16x16x32_bf16 v[110:113], v[160:163], v[194:197], v[110:113]
	v_mfma_f32_16x16x32_bf16 v[118:121], v[152:155], v[194:197], v[118:121]
	v_mfma_f32_16x16x32_bf16 v[118:121], v[148:151], v[190:193], v[118:121]
	v_mfma_f32_16x16x32_bf16 v[102:105], v[148:151], v[198:201], v[102:105]
	v_mfma_f32_16x16x32_bf16 v[102:105], v[152:155], v[202:205], v[102:105]
	v_mfma_f32_16x16x32_bf16 v[94:97], v[160:163], v[202:205], v[94:97]
	v_mfma_f32_16x16x32_bf16 v[94:97], v[156:159], v[198:201], v[94:97]
	v_mfma_f32_16x16x32_bf16 v[78:81], v[156:159], v[206:209], v[78:81]
	v_mfma_f32_16x16x32_bf16 v[78:81], v[160:163], v[210:213], v[78:81]
	v_mfma_f32_16x16x32_bf16 v[86:89], v[152:155], v[210:213], v[86:89]
	v_mfma_f32_16x16x32_bf16 v[86:89], v[148:151], v[206:209], v[86:89]
	s_setprio 0
	s_setprio 1
	v_mfma_f32_16x16x32_bf16 v[70:73], v[164:167], v[206:209], v[70:73]
	v_mfma_f32_16x16x32_bf16 v[70:73], v[168:171], v[210:213], v[70:73]
	v_mfma_f32_16x16x32_bf16 v[66:69], v[176:179], v[210:213], v[66:69]
	v_mfma_f32_16x16x32_bf16 v[66:69], v[172:175], v[206:209], v[66:69]
	v_mfma_f32_16x16x32_bf16 v[74:77], v[172:175], v[198:201], v[74:77]
	v_mfma_f32_16x16x32_bf16 v[74:77], v[176:179], v[202:205], v[74:77]
	v_mfma_f32_16x16x32_bf16 v[82:85], v[168:171], v[202:205], v[82:85]
	v_mfma_f32_16x16x32_bf16 v[82:85], v[164:167], v[198:201], v[82:85]
	v_mfma_f32_16x16x32_bf16 v[98:101], v[164:167], v[190:193], v[98:101]
	v_mfma_f32_16x16x32_bf16 v[98:101], v[168:171], v[194:197], v[98:101]
	v_mfma_f32_16x16x32_bf16 v[90:93], v[176:179], v[194:197], v[90:93]
	v_mfma_f32_16x16x32_bf16 v[90:93], v[172:175], v[190:193], v[90:93]
	v_mfma_f32_16x16x32_bf16 v[106:109], v[172:175], v[182:185], v[106:109]
	v_mfma_f32_16x16x32_bf16 v[106:109], v[176:179], v[186:189], v[106:109]
	v_mfma_f32_16x16x32_bf16 v[114:117], v[168:171], v[186:189], v[114:117]
	v_mfma_f32_16x16x32_bf16 v[114:117], v[164:167], v[182:185], v[114:117]
	s_setprio 0
	s_barrier
; #define PG8_STAGE(bufoff, gbase, voff) do { _Pragma("unroll") for (int _i = 0; _i < 2; ++_i) \
;         __builtin_amdgcn_global_load_lds((const unsigned*)((const char*)(gbase) + (voff)[_i]), (PG8_LAS unsigned*)(lds + (bufoff) + ldsw + _i * 8192), 16, 0, 0); } while (0)
; #define PG8_LDA(dst, b, h) do { _Pragma("unroll") for (int m = 0; m < 4; ++m) _Pragma("unroll") for (int k = 0; k < 2; ++k) dst[m][k] = *(const PG8_LAS bf16x8*)(lds + PG8_SA(b, h) + aoff + m * 2048 + k * 1024); } while (0)
; #define PG8_MMA(ai, bj, At, Bt) do { __builtin_amdgcn_s_setprio(1); _Pragma("unroll") for (int m = 0; m < 4; ++m) _Pragma("unroll") for (int n = 0; n < 2; ++n) _Pragma("unroll") for (int k = 0; k < 2; ++k) \
;         acc[ai][bj][m][n] = __builtin_amdgcn_mfma_f32_16x16x32_bf16(Bt[n][k], At[m][k], acc[ai][bj][m][n], 0, 0, 0); __builtin_amdgcn_s_setprio(0); } while (0)
; #define PG8_WAIT_V(n) asm volatile("s_waitcnt vmcnt(" #n ")" ::: "memory")
; #define PG8_WAIT_L(n) asm volatile("s_waitcnt lgkmcnt(" #n ")" ::: "memory")
; #define PG8_BAR __builtin_amdgcn_s_barrier()
; #define PG8_SCHED __builtin_amdgcn_sched_barrier(0)
; template <class Epi, class Sched, bool ALIGN_EPI = false, bool SP2 = false, bool RS = false, bool BPRE = false>
; __device__ __forceinline__ void gemm_phase(PG8_LAS unsigned char* lds, const Gemm g, const Sched& S, const Epi& E, const float* rs_ss = nullptr, PG8_LAS float* rs_tab = nullptr) {
;     ...
;             PG8_LDA(At, 1, 1); PG8_STAGE(PG8_SB(1, 0), b3, voffB); PG8_STAGE(PG8_SB(1, 1), b3 + hstep, voffB); PG8_STAGE(PG8_SA(1, 0), a3, voffA);
;             PG8_WAIT_V(8); PG8_WAIT_L(0); PG8_BAR; PG8_MMA(1, 0, At, B0); PG8_MMA(1, 1, At, B1); PG8_BAR; PG8_SCHED;
	s_add_u32 s20, s18, 0x4000
	s_addc_u32 s21, s19, 0
	s_mov_b32 m0, s71
	v_lshl_add_u64 v[180:181], s[20:21], 0, v[132:133]
	s_add_u32 s18, s18, 0x84000
	ds_read_b128 v[182:185], v145 offset:49152
	ds_read_b128 v[186:189], v145 offset:50176
	ds_read_b128 v[190:193], v145 offset:51200
	ds_read_b128 v[194:197], v145 offset:52224
	ds_read_b128 v[198:201], v145 offset:53248
	ds_read_b128 v[202:205], v145 offset:54272
	ds_read_b128 v[206:209], v145 offset:55296
	ds_read_b128 v[210:213], v145 offset:56320
	global_load_lds_dwordx4 v[180:181], off
	v_lshl_add_u64 v[180:181], s[20:21], 0, v[138:139]
	s_mov_b32 m0, s72
	s_addc_u32 s19, s19, 0
	global_load_lds_dwordx4 v[180:181], off
	v_lshl_add_u64 v[180:181], s[18:19], 0, v[132:133]
	s_mov_b32 m0, s73
	s_nop 0
	global_load_lds_dwordx4 v[180:181], off
	v_lshl_add_u64 v[180:181], s[18:19], 0, v[138:139]
	s_mov_b32 m0, s74
	s_nop 0
	global_load_lds_dwordx4 v[180:181], off
	v_lshl_add_u64 v[180:181], s[16:17], 0, v[130:131]
	s_mov_b32 m0, s46
	s_nop 0
	global_load_lds_dwordx4 v[180:181], off
	v_lshl_add_u64 v[180:181], s[16:17], 0, v[134:135]
	s_mov_b32 m0, s47
	s_nop 0
	global_load_lds_dwordx4 v[180:181], off
	s_waitcnt vmcnt(8)
	s_waitcnt lgkmcnt(0)
	s_barrier
	s_setprio 1
	s_waitcnt lgkmcnt(0)
	v_mfma_f32_16x16x32_bf16 v[62:65], v[148:151], v[182:185], v[62:65]
	v_mfma_f32_16x16x32_bf16 v[62:65], v[152:155], v[186:189], v[62:65]
	v_mfma_f32_16x16x32_bf16 v[58:61], v[160:163], v[186:189], v[58:61]
	v_mfma_f32_16x16x32_bf16 v[58:61], v[156:159], v[182:185], v[58:61]
	v_mfma_f32_16x16x32_bf16 v[46:49], v[156:159], v[190:193], v[46:49]
	v_mfma_f32_16x16x32_bf16 v[46:49], v[160:163], v[194:197], v[46:49]
	v_mfma_f32_16x16x32_bf16 v[54:57], v[152:155], v[194:197], v[54:57]
	v_mfma_f32_16x16x32_bf16 v[54:57], v[148:151], v[190:193], v[54:57]
	v_mfma_f32_16x16x32_bf16 v[38:41], v[148:151], v[198:201], v[38:41]
	v_mfma_f32_16x16x32_bf16 v[38:41], v[152:155], v[202:205], v[38:41]
	v_mfma_f32_16x16x32_bf16 v[30:33], v[160:163], v[202:205], v[30:33]
	v_mfma_f32_16x16x32_bf16 v[30:33], v[156:159], v[198:201], v[30:33]
	v_mfma_f32_16x16x32_bf16 v[14:17], v[156:159], v[206:209], v[14:17]
	v_mfma_f32_16x16x32_bf16 v[14:17], v[160:163], v[210:213], v[14:17]
	v_mfma_f32_16x16x32_bf16 v[22:25], v[152:155], v[210:213], v[22:25]
	v_mfma_f32_16x16x32_bf16 v[22:25], v[148:151], v[206:209], v[22:25]
	s_setprio 0
	s_setprio 1
	v_mfma_f32_16x16x32_bf16 v[6:9], v[164:167], v[206:209], v[6:9]
	v_mfma_f32_16x16x32_bf16 v[6:9], v[168:171], v[210:213], v[6:9]
	v_mfma_f32_16x16x32_bf16 v[2:5], v[176:179], v[210:213], v[2:5]
	v_mfma_f32_16x16x32_bf16 v[2:5], v[172:175], v[206:209], v[2:5]
	v_mfma_f32_16x16x32_bf16 v[10:13], v[172:175], v[198:201], v[10:13]
	v_mfma_f32_16x16x32_bf16 v[10:13], v[176:179], v[202:205], v[10:13]
	v_mfma_f32_16x16x32_bf16 v[18:21], v[168:171], v[202:205], v[18:21]
	v_mfma_f32_16x16x32_bf16 v[18:21], v[164:167], v[198:201], v[18:21]
	v_mfma_f32_16x16x32_bf16 v[34:37], v[164:167], v[190:193], v[34:37]
	v_mfma_f32_16x16x32_bf16 v[34:37], v[168:171], v[194:197], v[34:37]
	v_mfma_f32_16x16x32_bf16 v[26:29], v[176:179], v[194:197], v[26:29]
	v_mfma_f32_16x16x32_bf16 v[26:29], v[172:175], v[190:193], v[26:29]
	v_mfma_f32_16x16x32_bf16 v[42:45], v[172:175], v[182:185], v[42:45]
	v_mfma_f32_16x16x32_bf16 v[42:45], v[176:179], v[186:189], v[42:45]
	v_mfma_f32_16x16x32_bf16 v[50:53], v[168:171], v[186:189], v[50:53]
	v_mfma_f32_16x16x32_bf16 v[50:53], v[164:167], v[182:185], v[50:53]
	s_setprio 0
	s_barrier
	s_add_i32 s56, s56, 2
	s_add_u32 s14, s14, 0x8000
	s_addc_u32 s15, s15, 0
	s_cmp_gt_u32 s56, 29
	s_cbranch_scc0 .LBB0_129
; __device__ __forceinline__ unsigned cvt_pk_bf16(float lo, float hi) { unsigned r; asm volatile("v_cvt_pk_bf16_f32 %0, %1, %2" : "=v"(r) : "v"(lo), "v"(hi)); return r; }
;     __device__ __forceinline__ void operator()(const f32x4 (&acc)[2][2][4][2], const pg8::Unit& u, int wr, int wc, int fr, int fq, const LAS float* tab) const {
;     ...
;         else if (mode == 1) { ldc = 256; if (pm >= 8) { pm -= 8; } else { pm -= 4; pn -= 8; base = O2; } base += (size_t)(pm * 4 + pn) * 65536; pm = 0; pn = 0; }
;         else { ldc = DMODEL; kind = 4; }
;         int col0 = pn * 256 + wc * 32 + 8 * fq; const int row0 = pm * 256 + wr * 64 + fr;
;         if (mode == 0) { ldc = 256; base = O + (size_t)pn * NTOK * 256; col0 = wc * 32 + 8 * fq; }
; #pragma unroll
;         for (int ai = 0; ai < 2; ++ai)
; #pragma unroll
;             for (int m = 0; m < 4; ++m) {
;                 const int row = row0 + ai * 128 + m * 16;
;                 bf16_t* rowp = (mode == 0) ? base + (size_t)(row >> 4) * 4096 + (size_t)(wc * 512 + (row & 15) * 32 + 8 * fq) : base + (size_t)row * ldc + col0;
;                 const int bjstep = (mode == 0) ? 4 * 512 : 128;
;                 float s1 = 0.f, s2 = 0.f;
;                 const float f2 = (kind == 4) ? tab[512 + ai * 128 + wr * 64 + m * 16 + fr] : 1.0f;
; #pragma unroll
;                 for (int bj = 0; bj < 2; ++bj) {
;                     f32x4 v0 = acc[ai][bj][m][0], v1 = acc[ai][bj][m][1];
;                     if (kind == 1) {
; #pragma unroll
;                         for (int e = 0; e < 4; ++e) { v0[e] = silu_f(v0[e]); v1[e] = silu_f(v1[e]); }
;                     } else if (kind == 2) { v0 = v0 * QSCALE; v1 = v1 * QSCALE; }
;                     else if (kind == 3) {
; #pragma unroll
;                         for (int e = 0; e < 4; ++e) { s1 += v0[e] + v1[e]; s2 += v0[e] * v0[e] + v1[e] * v1[e]; }
;                     } else if (kind == 4) {
;                         v0 = v0 * f2; v1 = v1 * f2;
; #pragma unroll
;                         for (int e = 0; e < 4; ++e) s2 += v0[e] * v0[e] + v1[e] * v1[e];
;                     }
;                     u32x4 w; w.x = cvt_pk_bf16(v0[0], v0[1]); w.y = cvt_pk_bf16(v0[2], v0[3]); w.z = cvt_pk_bf16(v1[0], v1[1]); w.w = cvt_pk_bf16(v1[2], v1[3]);
;                     *(u32x4*)(rowp + bj * bjstep) = w;
	s_cmp_gt_u32 s0, 7
	s_cselect_b64 s[6:7], -1, 0
	s_add_i32 s1, s4, -8
	s_and_b64 s[6:7], s[6:7], exec
	s_cselect_b32 s1, s4, s1
	s_cselect_b32 s4, -8, -4
	s_cselect_b32 s5, s41, s43
	s_cselect_b32 s6, s40, s42
	s_add_i32 s4, s4, s0
	s_lshl_b32 s0, s4, 2
	s_add_i32 s0, s0, s1
	s_ashr_i32 s1, s0, 31
	s_lshl_b64 s[0:1], s[0:1], 17
	s_add_u32 s0, s6, s0
	v_mov_b32_e32 v131, 0
	s_addc_u32 s1, s5, s1
	v_lshl_or_b32 v130, s37, 6, v1
	v_mov_b32_e32 v137, v131
	v_lshl_add_u64 v[132:133], s[0:1], 0, v[130:131]
	v_lshlrev_b64 v[134:135], 9, v[136:137]
	v_lshl_add_u64 v[134:135], v[132:133], 0, v[134:135]
	v_or_b32_e32 v130, 16, v136
	v_cvt_pk_bf16_f32 v126, v126, v127
	v_cvt_pk_bf16_f32 v127, v128, v129
	v_cvt_pk_bf16_f32 v128, v122, v123
	v_cvt_pk_bf16_f32 v129, v124, v125
	global_store_dwordx4 v[134:135], v[126:129], off
	v_cvt_pk_bf16_f32 v114, v114, v115
	v_cvt_pk_bf16_f32 v115, v116, v117
	v_cvt_pk_bf16_f32 v116, v106, v107
	v_lshlrev_b64 v[106:107], 9, v[130:131]
	v_cvt_pk_bf16_f32 v117, v108, v109
	global_store_dwordx4 v[134:135], v[114:117], off offset:256
	v_or_b32_e32 v130, 32, v136
	s_cmpk_lt_u32 s36, 0x100
	v_lshl_add_u64 v[114:115], v[132:133], 0, v[106:107]
	v_cvt_pk_bf16_f32 v106, v118, v119
	v_cvt_pk_bf16_f32 v107, v120, v121
	v_cvt_pk_bf16_f32 v108, v110, v111
	v_cvt_pk_bf16_f32 v109, v112, v113
	global_store_dwordx4 v[114:115], v[106:109], off
	v_cvt_pk_bf16_f32 v98, v98, v99
	v_cvt_pk_bf16_f32 v99, v100, v101
	v_cvt_pk_bf16_f32 v100, v90, v91
	v_lshlrev_b64 v[90:91], 9, v[130:131]
	v_cvt_pk_bf16_f32 v101, v92, v93
	global_store_dwordx4 v[114:115], v[98:101], off offset:256
	v_or_b32_e32 v130, 48, v136
	s_nop 0
	v_lshl_add_u64 v[98:99], v[132:133], 0, v[90:91]
	v_cvt_pk_bf16_f32 v90, v102, v103
	v_cvt_pk_bf16_f32 v91, v104, v105
	v_cvt_pk_bf16_f32 v92, v94, v95
	v_cvt_pk_bf16_f32 v93, v96, v97
	global_store_dwordx4 v[98:99], v[90:93], off
	v_cvt_pk_bf16_f32 v82, v82, v83
	v_cvt_pk_bf16_f32 v83, v84, v85
	v_cvt_pk_bf16_f32 v84, v74, v75
	v_lshlrev_b64 v[74:75], 9, v[130:131]
	v_cvt_pk_bf16_f32 v85, v76, v77
	global_store_dwordx4 v[98:99], v[82:85], off offset:256
	v_add_u32_e32 v130, 0x80, v136
	s_nop 0
	v_lshl_add_u64 v[82:83], v[132:133], 0, v[74:75]
	v_cvt_pk_bf16_f32 v74, v86, v87
	v_cvt_pk_bf16_f32 v75, v88, v89
	v_cvt_pk_bf16_f32 v76, v78, v79
	v_cvt_pk_bf16_f32 v77, v80, v81
	global_store_dwordx4 v[82:83], v[74:77], off
	v_cvt_pk_bf16_f32 v70, v70, v71
	v_cvt_pk_bf16_f32 v71, v72, v73
	v_cvt_pk_bf16_f32 v72, v66, v67
	v_lshlrev_b64 v[66:67], 9, v[130:131]
	v_lshl_add_u64 v[66:67], v[132:133], 0, v[66:67]
	v_add_u32_e32 v130, 0x90, v136
	v_cvt_pk_bf16_f32 v73, v68, v69
	global_store_dwordx4 v[82:83], v[70:73], off offset:256
	v_cvt_pk_bf16_f32 v62, v62, v63
	v_cvt_pk_bf16_f32 v63, v64, v65
	v_cvt_pk_bf16_f32 v64, v58, v59
	v_cvt_pk_bf16_f32 v65, v60, v61
	global_store_dwordx4 v[66:67], v[62:65], off
	v_cvt_pk_bf16_f32 v50, v50, v51
	v_cvt_pk_bf16_f32 v51, v52, v53
	v_cvt_pk_bf16_f32 v52, v42, v43
	v_lshlrev_b64 v[42:43], 9, v[130:131]
	v_cvt_pk_bf16_f32 v53, v44, v45
	global_store_dwordx4 v[66:67], v[50:53], off offset:256
	v_add_u32_e32 v130, 0xa0, v136
	s_nop 0
	v_lshl_add_u64 v[50:51], v[132:133], 0, v[42:43]
	v_cvt_pk_bf16_f32 v42, v54, v55
	v_cvt_pk_bf16_f32 v43, v56, v57
	v_cvt_pk_bf16_f32 v44, v46, v47
	v_cvt_pk_bf16_f32 v45, v48, v49
	global_store_dwordx4 v[50:51], v[42:45], off
	v_cvt_pk_bf16_f32 v34, v34, v35
	v_cvt_pk_bf16_f32 v35, v36, v37
	v_cvt_pk_bf16_f32 v36, v26, v27
	v_lshlrev_b64 v[26:27], 9, v[130:131]
	v_cvt_pk_bf16_f32 v37, v28, v29
	global_store_dwordx4 v[50:51], v[34:37], off offset:256
	v_add_u32_e32 v130, 0xb0, v136
	s_nop 0
	v_lshl_add_u64 v[34:35], v[132:133], 0, v[26:27]
	v_cvt_pk_bf16_f32 v26, v38, v39
	v_cvt_pk_bf16_f32 v27, v40, v41
	v_cvt_pk_bf16_f32 v28, v30, v31
	v_cvt_pk_bf16_f32 v29, v32, v33
	global_store_dwordx4 v[34:35], v[26:29], off
	v_cvt_pk_bf16_f32 v18, v18, v19
	v_cvt_pk_bf16_f32 v19, v20, v21
	v_cvt_pk_bf16_f32 v20, v10, v11
	v_lshlrev_b64 v[10:11], 9, v[130:131]
	v_cvt_pk_bf16_f32 v21, v12, v13
	global_store_dwordx4 v[34:35], v[18:21], off offset:256
	s_nop 1
	v_lshl_add_u64 v[18:19], v[132:133], 0, v[10:11]
	v_cvt_pk_bf16_f32 v10, v22, v23
	v_cvt_pk_bf16_f32 v11, v24, v25
	v_cvt_pk_bf16_f32 v12, v14, v15
	v_cvt_pk_bf16_f32 v13, v16, v17
	global_store_dwordx4 v[18:19], v[10:13], off
	v_cvt_pk_bf16_f32 v6, v6, v7
	v_cvt_pk_bf16_f32 v7, v8, v9
	v_cvt_pk_bf16_f32 v8, v2, v3
	v_cvt_pk_bf16_f32 v9, v4, v5
	global_store_dwordx4 v[18:19], v[6:9], off offset:256
	s_waitcnt vmcnt(0)
	s_cbranch_scc0 .LBB0_132
	s_barrier
